# dead m0 save/restore pairs dropped from the relocated MLA LDS-DMA blocks (12 SALU fewer on the tile's critical path); on the DMA-relocation stack
# baseline (speedup 1.0000x reference)
.LBB0_1221:
	s_or_b32 s86, s51, s50
	s_cmp_gt_u32 s86, s57
	s_cbranch_scc1 .LBB0_1220
	v_or_b32_e32 v5, s51, v203
	s_movk_i32 s87, 0x190
	v_mad_u32_u24 v5, v5, s87, v3
	ds_read_b128 v[6:9], v5
	ds_read_b128 v[10:13], v5 offset:32
	ds_read_b128 v[14:17], v5 offset:64
	ds_read_b128 v[216:219], v5 offset:96
	ds_read_b128 v[220:223], v5 offset:128
	ds_read_b128 v[224:227], v5 offset:160
	ds_read_b128 v[228:231], v5 offset:192
	ds_read_b128 v[232:235], v5 offset:224
	s_cmp_lg_u32 s51, 0
	s_cbranch_scc1 .Lmla_nodma
	s_cmp_gt_i32 s55, 0
	s_cselect_b32 s98, -1, 2
	s_add_i32 s100, s98, s55
	s_add_i32 s98, s93, 2
	s_min_u32 s98, s98, s56
	s_mul_i32 s99, s98, 0x60000
	s_add_u32 s86, s92, s99
	s_addc_u32 s87, s54, 0
	s_lshl_b32 s98, s98, 18
	s_add_u32 s98, s80, s98
	s_mul_i32 s100, s100, 0xb400
	s_addc_u32 s99, s81, 0
	s_add_i32 vcc_lo, s100, 0
	s_and_b64 s[100:101], s[30:31], exec
	s_cselect_b32 s101, s87, s99
	s_cselect_b32 s100, s86, s98
	v_lshl_add_u64 v[238:239], s[100:101], 0, v[166:167]
	s_add_i32 s100, vcc_lo, s20
	s_mov_b32 m0, s100
	s_nop 0
	global_load_lds_dwordx4 v[238:239], off
	s_and_b64 s[100:101], s[52:53], exec
	s_cselect_b32 s101, s87, s99
	s_cselect_b32 s100, s86, s98
	v_lshl_add_u64 v[238:239], s[100:101], 0, v[146:147]
	s_add_i32 s100, vcc_lo, s26
	s_mov_b32 m0, s100
	s_nop 0
	global_load_lds_dwordx4 v[238:239], off
	s_and_b64 s[100:101], s[72:73], exec
	s_cselect_b32 s101, s87, s99
	s_cselect_b32 s100, s86, s98
	v_lshl_add_u64 v[238:239], s[100:101], 0, v[148:149]
	s_add_i32 s100, vcc_lo, s36
	s_mov_b32 m0, s100
	s_nop 0
	global_load_lds_dwordx4 v[238:239], off
	s_and_b64 s[100:101], s[74:75], exec
	s_cselect_b32 s101, s87, s99
	s_cselect_b32 s100, s86, s98
	v_lshl_add_u64 v[238:239], s[100:101], 0, v[150:151]
	s_add_i32 s100, vcc_lo, s38
	s_mov_b32 m0, s100
	s_nop 0
	global_load_lds_dwordx4 v[238:239], off
	s_and_b64 s[100:101], s[76:77], exec
	s_cselect_b32 s101, s87, s99
	s_cselect_b32 s100, s86, s98
	v_lshl_add_u64 v[238:239], s[100:101], 0, v[168:169]
	s_add_i32 s100, vcc_lo, s88
	s_mov_b32 m0, s100
	s_nop 0
	global_load_lds_dwordx4 v[238:239], off
	s_add_i32 vcc_lo, vcc_lo, s90
	v_lshl_add_u64 v[238:239], s[98:99], 0, v[152:153]
	s_mov_b32 m0, vcc_lo
	s_nop 0
	global_load_lds_dwordx4 v[238:239], off
	s_or_b32 s86, s51, s50

.Lmla_skiptile:
	s_cmp_gt_i32 s55, 0
	s_cselect_b32 s98, -1, 2
	s_add_i32 s100, s98, s55
	s_add_i32 s98, s93, 2
	s_min_u32 s98, s98, s56
	s_mul_i32 s99, s98, 0x60000
	s_add_u32 s86, s92, s99
	s_addc_u32 s87, s54, 0
	s_lshl_b32 s98, s98, 18
	s_add_u32 s98, s80, s98
	s_mul_i32 s100, s100, 0xb400
	s_addc_u32 s99, s81, 0
	s_add_i32 vcc_lo, s100, 0
	s_and_b64 s[100:101], s[30:31], exec
	s_cselect_b32 s101, s87, s99
	s_cselect_b32 s100, s86, s98
	v_lshl_add_u64 v[238:239], s[100:101], 0, v[166:167]
	s_add_i32 s100, vcc_lo, s20
	s_mov_b32 m0, s100
	s_nop 0
	global_load_lds_dwordx4 v[238:239], off
	s_and_b64 s[100:101], s[52:53], exec
	s_cselect_b32 s101, s87, s99
	s_cselect_b32 s100, s86, s98
	v_lshl_add_u64 v[238:239], s[100:101], 0, v[146:147]
	s_add_i32 s100, vcc_lo, s26
	s_mov_b32 m0, s100
	s_nop 0
	global_load_lds_dwordx4 v[238:239], off
	s_and_b64 s[100:101], s[72:73], exec
	s_cselect_b32 s101, s87, s99
	s_cselect_b32 s100, s86, s98
	v_lshl_add_u64 v[238:239], s[100:101], 0, v[148:149]
	s_add_i32 s100, vcc_lo, s36
	s_mov_b32 m0, s100
	s_nop 0
	global_load_lds_dwordx4 v[238:239], off
	s_and_b64 s[100:101], s[74:75], exec
	s_cselect_b32 s101, s87, s99
	s_cselect_b32 s100, s86, s98
	v_lshl_add_u64 v[238:239], s[100:101], 0, v[150:151]
	s_add_i32 s100, vcc_lo, s38
	s_mov_b32 m0, s100
	s_nop 0
	global_load_lds_dwordx4 v[238:239], off
	s_and_b64 s[100:101], s[76:77], exec
	s_cselect_b32 s101, s87, s99
	s_cselect_b32 s100, s86, s98
	v_lshl_add_u64 v[238:239], s[100:101], 0, v[168:169]
	s_add_i32 s100, vcc_lo, s88
	s_mov_b32 m0, s100
	s_nop 0
	global_load_lds_dwordx4 v[238:239], off
	s_add_i32 vcc_lo, vcc_lo, s90
	v_lshl_add_u64 v[238:239], s[98:99], 0, v[152:153]
	s_mov_b32 m0, vcc_lo
	s_nop 0
	global_load_lds_dwordx4 v[238:239], off
